# P4 sliding-window branch: 8 waves share each K/V tile via LDS-DMA 3-stage ring + 1 barrier per tile (instead of per-wave L2 loads); plus GEMM k-loop DMA interleave
# speedup vs baseline: 1.0339x; 1.0154x over previous
.LBB0_607:
	s_or_b64 exec, exec, s[16:17]
	v_lshl_add_u64 v[2:3], v[204:205], 2, s[52:53]
	global_load_dword v56, v[2:3], off
	global_load_dwordx4 v[12:15], v[148:149], off offset:64
	global_load_dwordx4 v[16:19], v[148:149], off
	ds_bpermute_b32 v4, v223, v237
	ds_read2st64_b32 v[8:9], v213 offset1:1
	ds_read2st64_b32 v[10:11], v213 offset0:2 offset1:3
	ds_read2st64_b32 v[54:55], v213 offset0:4 offset1:5
	ds_read_b32 v57, v213 offset:1536
	v_max_i32_e32 v5, 0x1ff, v227
	v_mov_b32_e32 v2, v0
	v_mov_b32_e32 v3, v0
	s_waitcnt lgkmcnt(4)
	v_add_f32_e32 v58, v237, v4
	ds_bpermute_b32 v59, v224, v58
	v_add_u32_e32 v48, 0xfffffe01, v5
	v_mov_b32_e32 v1, v0
	v_mov_b64_e32 v[46:47], v[2:3]
	v_mov_b64_e32 v[22:23], v[2:3]
	s_waitcnt lgkmcnt(0)
	v_add_f32_e32 v58, v58, v59
	v_div_scale_f32 v59, s[0:1], v58, v58, 1.0
	v_rcp_f32_e32 v60, v59
	v_div_scale_f32 v61, vcc, 1.0, v58, 1.0
	v_mov_b64_e32 v[6:7], v[2:3]
	v_fma_f32 v62, -v59, v60, 1.0
	v_fmac_f32_e32 v60, v62, v60
	v_mul_f32_e32 v62, v61, v60
	v_fma_f32 v63, -v59, v62, v61
	v_fmac_f32_e32 v62, v63, v60
	v_fma_f32 v59, -v59, v62, v61
	v_div_fmas_f32 v59, v59, v60, v62
	v_div_fixup_f32 v59, v59, v58, 1.0
	v_cmp_lt_f32_e32 vcc, 0, v58
	v_lshrrev_b32_e32 v48, 6, v48
	v_mov_b32_e32 v234, 0
	v_cndmask_b32_e32 v58, 0, v59, vcc
	v_mov_b64_e32 v[44:45], v[0:1]
	v_mov_b64_e32 v[20:21], v[0:1]
	v_mov_b64_e32 v[4:5], v[0:1]
	v_cmp_le_i32_e64 s[0:1], v48, v229
	s_waitcnt vmcnt(2)
	v_mul_f32_e32 v56, v56, v58
	v_fma_f32 v8, v56, v40, v8
	v_fmac_f32_e32 v9, v56, v41
	v_fma_f32 v10, v56, v42, v10
	v_fmac_f32_e32 v11, v56, v43
	v_fma_f32 v36, v56, v36, v54
	v_fmac_f32_e32 v55, v56, v37
	v_fmac_f32_e32 v57, v56, v38
	v_fmac_f32_e32 v49, v56, v39
	v_fmac_f32_e32 v52, v56, v32
	v_fmac_f32_e32 v53, v56, v33
	v_fmac_f32_e32 v26, v56, v34
	v_fmac_f32_e32 v27, v56, v35
	v_fmac_f32_e32 v50, v56, v28
	v_fmac_f32_e32 v51, v56, v29
	v_fmac_f32_e32 v24, v56, v30
	v_fmac_f32_e32 v25, v56, v31
	ds_write2st64_b32 v213, v8, v9 offset1:1
	ds_write2st64_b32 v213, v10, v11 offset0:2 offset1:3
	ds_write2st64_b32 v213, v36, v55 offset0:4 offset1:5
	ds_write2st64_b32 v213, v57, v49 offset0:6 offset1:7
	ds_write2st64_b32 v213, v52, v53 offset0:8 offset1:9
	ds_write2st64_b32 v213, v26, v27 offset0:10 offset1:11
	ds_write2st64_b32 v213, v50, v51 offset0:12 offset1:13
	ds_write2st64_b32 v213, v24, v25 offset0:14 offset1:15
	v_mov_b64_e32 v[10:11], v[2:3]
	v_mov_b64_e32 v[8:9], v[0:1]
	s_waitcnt vmcnt(0)
	s_and_saveexec_b64 s[14:15], s[0:1]
	s_cbranch_execz .LBB0_422
	v_mov_b32_e32 v2, v0
	v_mov_b32_e32 v3, v0
	v_mov_b32_e32 v1, v0
	v_mov_b64_e32 v[46:47], v[2:3]
	v_mov_b64_e32 v[22:23], v[2:3]
	v_mov_b64_e32 v[6:7], v[2:3]
	v_mov_b64_e32 v[10:11], v[2:3]
	v_mov_b64_e32 v[44:45], v[0:1]
	v_mov_b64_e32 v[20:21], v[0:1]
	v_mov_b64_e32 v[4:5], v[0:1]
	v_mov_b64_e32 v[8:9], v[0:1]
	v_add_u32_e32 v231, 0xfffffe04, v227
	v_add_u32_e32 v232, 0xfffffe01, v228
	v_mov_b32_e32 v235, 0xf149f2ca
	v_mov_b32_e32 v236, 0
	v_readfirstlane_b32 s32, v227
	v_readfirstlane_b32 s22, v48
	v_readfirstlane_b32 s24, v229
	v_readfirstlane_b32 s75, v191
	v_and_b32_e32 v60, 63, v191
	v_lshlrev_b32_e32 v60, 4, v60
	s_mov_b32 s95, 0
	s_lshl_b32 s75, s75, 4
	s_and_b32 s93, s32, 0xffffffe0
	s_max_i32 s12, s93, 0x1ff
	s_sub_i32 s12, s12, 0x1ff
	s_lshr_b32 s12, s12, 6
	s_add_i32 s13, s93, 31
	s_lshr_b32 s13, s13, 6
	s_mov_b32 s36, 0x10010
	s_mov_b32 s37, 0x14010
	s_mov_b32 s72, 0x18010
	s_mov_b32 s94, s75
	s_add_i32 s98, s32, 0xfffffe04
	v_lshl_add_u64 v[64:65], v[186:187], 0, s[94:95]
	v_lshl_add_u64 v[66:67], v[188:189], 0, s[94:95]
	s_barrier
	s_lshl_b32 s94, s12, 13
	s_add_i32 m0, s36, s75
	v_lshl_add_u64 v[62:63], v[64:65], 0, s[94:95]
	s_add_i32 s93, s36, 0x2000
	global_load_lds_dwordx4 v[62:63], off
	v_lshl_add_u64 v[62:63], v[66:67], 0, s[94:95]
	s_add_i32 m0, s93, s75
	s_nop 0
	global_load_lds_dwordx4 v[62:63], off
	s_cmp_lt_i32 s12, s13
	s_cbranch_scc0 .Lwin_loop
	s_add_i32 s99, s12, 1
	s_lshl_b32 s94, s99, 13
	s_add_i32 m0, s37, s75
	v_lshl_add_u64 v[62:63], v[64:65], 0, s[94:95]
	s_add_i32 s93, s37, 0x2000
	global_load_lds_dwordx4 v[62:63], off
	v_lshl_add_u64 v[62:63], v[66:67], 0, s[94:95]
	s_add_i32 m0, s93, s75
	s_nop 0
	global_load_lds_dwordx4 v[62:63], off
.Lwin_loop:
	s_cmp_lt_i32 s12, s13
	s_cbranch_scc1 .Lwin_w2
	s_waitcnt vmcnt(0)
	s_branch .Lwin_bar
.Lwin_w2:
	s_waitcnt vmcnt(2)
.Lwin_bar:
	s_barrier
	s_add_i32 s99, s12, 2
	s_cmp_le_i32 s99, s13
	s_cbranch_scc0 .Lwin_nodma
	s_lshl_b32 s94, s99, 13
	s_add_i32 m0, s72, s75
	v_lshl_add_u64 v[62:63], v[64:65], 0, s[94:95]
	s_add_i32 s93, s72, 0x2000
	global_load_lds_dwordx4 v[62:63], off
	v_lshl_add_u64 v[62:63], v[66:67], 0, s[94:95]
	s_add_i32 m0, s93, s75
	s_nop 0
	global_load_lds_dwordx4 v[62:63], off
.Lwin_nodma:
	s_cmp_lt_i32 s12, s22
	s_cbranch_scc1 .Lwin_skip
	s_cmp_gt_i32 s12, s24
	s_cbranch_scc1 .Lwin_skip
	v_add_u32_e32 v61, s36, v60
	ds_read_b128 v[120:123], v61
	ds_read_b128 v[116:119], v61 offset:1024
	ds_read_b128 v[112:115], v61 offset:2048
	ds_read_b128 v[108:111], v61 offset:3072
	ds_read_b128 v[104:107], v61 offset:4096
	ds_read_b128 v[100:103], v61 offset:5120
	ds_read_b128 v[96:99], v61 offset:6144
	ds_read_b128 v[92:95], v61 offset:7168
	ds_read_b128 v[56:59], v61 offset:8192
	ds_read_b128 v[52:55], v61 offset:9216
	ds_read_b128 v[48:51], v61 offset:10240
	ds_read_b128 v[40:43], v61 offset:11264
	ds_read_b128 v[36:39], v61 offset:12288
	ds_read_b128 v[32:35], v61 offset:13312
	ds_read_b128 v[28:31], v61 offset:14336
	ds_read_b128 v[24:27], v61 offset:15360
	s_lshl_b32 s93, s12, 6
	v_mov_b32_e32 v230, s93
	v_add_u32_e32 v230, 0x7f, v230
	s_add_i32 s99, s93, 63
	s_waitcnt lgkmcnt(0)
	s_cmp_ge_i32 s93, s98
	s_cbranch_scc0 .Lwin_msk
	s_cmp_le_i32 s99, s32
	s_cbranch_scc0 .Lwin_msk
	v_mfma_f32_16x16x32_bf16 v[120:123], v[120:123], v[16:19], 0
	v_mfma_f32_16x16x32_bf16 v[112:115], v[112:115], v[16:19], 0
	v_mfma_f32_16x16x32_bf16 v[116:119], v[116:119], v[12:15], v[120:123]
	v_mfma_f32_16x16x32_bf16 v[104:107], v[104:107], v[16:19], 0
	v_mfma_f32_16x16x32_bf16 v[108:111], v[108:111], v[12:15], v[112:115]
	s_nop 5
	v_max_f32_e32 v1, v117, v117
	v_max_f32_e32 v2, v116, v116
	v_max_f32_e32 v1, v2, v1
	v_mfma_f32_16x16x32_bf16 v[96:99], v[96:99], v[16:19], 0
	v_max_f32_e32 v2, v119, v119
	v_max_f32_e32 v3, v118, v118
	v_max_f32_e32 v2, v3, v2
	v_mfma_f32_16x16x32_bf16 v[100:103], v[100:103], v[12:15], v[104:107]
	v_max_f32_e32 v3, v111, v111
	v_max_f32_e32 v112, v110, v110
	v_max_f32_e32 v3, v112, v3
	v_mfma_f32_16x16x32_bf16 v[92:95], v[92:95], v[12:15], v[96:99]
	v_max3_f32 v3, v108, v109, v3
	v_max3_f32 v1, v1, v2, v3
	s_nop 1
	v_max_f32_e32 v2, v103, v103
	v_max_f32_e32 v3, v102, v102
	v_max_f32_e32 v2, v3, v2
	s_nop 0
	v_max_f32_e32 v3, v95, v95
	v_max_f32_e32 v96, v94, v94
	v_max_f32_e32 v3, v96, v3
	v_max3_f32 v2, v100, v101, v2
	v_max3_f32 v3, v92, v93, v3
	v_max3_f32 v1, v1, v2, v3
	ds_bpermute_b32 v2, v223, v1
	s_waitcnt lgkmcnt(0)
	v_max_f32_e32 v2, v2, v2
	v_max_f32_e32 v1, v1, v2
	ds_bpermute_b32 v2, v224, v1
	s_waitcnt lgkmcnt(0)
	v_max3_f32 v1, v235, v1, v2
	v_sub_f32_e32 v3, v116, v1
	v_exp_f32_e32 v3, v3
	v_sub_f32_e32 v96, v117, v1
	v_exp_f32_e32 v96, v96
	v_sub_f32_e32 v97, v118, v1
	v_exp_f32_e32 v97, v97
	v_sub_f32_e32 v98, v119, v1
	v_exp_f32_e32 v98, v98
	v_sub_f32_e32 v104, v108, v1
	v_add_f32_e32 v99, 0, v3
	v_exp_f32_e32 v104, v104
	v_sub_f32_e32 v105, v109, v1
	v_add_f32_e32 v99, v96, v99
	v_exp_f32_e32 v105, v105
	v_sub_f32_e32 v106, v110, v1
	v_add_f32_e32 v99, v97, v99
	v_exp_f32_e32 v106, v106
	v_sub_f32_e32 v107, v111, v1
	v_add_f32_e32 v99, v98, v99
	v_exp_f32_e32 v107, v107
	v_add_f32_e32 v99, v104, v99
	v_sub_f32_e32 v2, v235, v1
	v_add_f32_e32 v99, v105, v99
	v_sub_f32_e32 v92, v92, v1
	v_add_f32_e32 v99, v106, v99
	v_exp_f32_e32 v109, v92
	v_exp_f32_e32 v92, v2
	v_sub_f32_e32 v2, v93, v1
	v_add_f32_e32 v108, v107, v99
	v_sub_f32_e32 v99, v100, v1
	v_exp_f32_e32 v93, v2
	v_exp_f32_e32 v100, v99
	v_sub_f32_e32 v99, v101, v1
	v_exp_f32_e32 v101, v99
	v_sub_f32_e32 v99, v102, v1
	v_exp_f32_e32 v102, v99
	v_sub_f32_e32 v99, v103, v1
	v_exp_f32_e32 v103, v99
	v_cvt_pk_bf16_f32 v96, v3, v96
	v_cvt_pk_bf16_f32 v97, v97, v98
	v_cvt_pk_bf16_f32 v98, v104, v105
	v_cvt_pk_bf16_f32 v99, v106, v107
	v_pk_mul_f32 v[22:23], v[22:23], v[92:93] op_sel_hi:[1,0]
	v_pk_mul_f32 v[20:21], v[20:21], v[92:93] op_sel_hi:[1,0]
	v_sub_f32_e32 v2, v94, v1
	v_pk_mul_f32 v[46:47], v[46:47], v[92:93] op_sel_hi:[1,0]
	v_pk_mul_f32 v[44:45], v[44:45], v[92:93] op_sel_hi:[1,0]
	v_mfma_f32_16x16x32_bf16 v[20:23], v[52:55], v[96:99], v[20:23]
	v_sub_f32_e32 v52, v95, v1
	v_pk_mul_f32 v[6:7], v[6:7], v[92:93] op_sel_hi:[1,0]
	v_pk_mul_f32 v[4:5], v[4:5], v[92:93] op_sel_hi:[1,0]
	v_mfma_f32_16x16x32_bf16 v[44:47], v[56:59], v[96:99], v[44:47]
	v_exp_f32_e32 v56, v2
	v_pk_mul_f32 v[10:11], v[10:11], v[92:93] op_sel_hi:[1,0]
	v_pk_mul_f32 v[8:9], v[8:9], v[92:93] op_sel_hi:[1,0]
	v_mfma_f32_16x16x32_bf16 v[2:5], v[48:51], v[96:99], v[4:7]
	v_exp_f32_e32 v48, v52
	v_mov_b32_e32 v235, v1
	v_mfma_f32_16x16x32_bf16 v[8:11], v[40:43], v[96:99], v[8:11]
	v_add_f32_e32 v6, v100, v108
	v_add_f32_e32 v6, v101, v6
	v_add_f32_e32 v6, v102, v6
	v_add_f32_e32 v6, v103, v6
	v_cvt_pk_bf16_f32 v40, v100, v101
	v_cvt_pk_bf16_f32 v41, v102, v103
	v_cvt_pk_bf16_f32 v42, v109, v93
	v_cvt_pk_bf16_f32 v43, v56, v48
	v_add_f32_e32 v6, v109, v6
	s_nop 0
	v_mfma_f32_16x16x32_bf16 v[44:47], v[36:39], v[40:43], v[44:47]
	v_mfma_f32_16x16x32_bf16 v[20:23], v[32:35], v[40:43], v[20:23]
	v_add_f32_e32 v32, v93, v6
	v_mfma_f32_16x16x32_bf16 v[4:7], v[28:31], v[40:43], v[2:5]
	v_mfma_f32_16x16x32_bf16 v[8:11], v[24:27], v[40:43], v[8:11]
	s_nop 1
	v_add_f32_e32 v2, v56, v32
	v_add_f32_e32 v234, v48, v2
	v_fmac_f32_e32 v234, v236, v92
	s_branch .Lwin_join
.Lwin_msk:
	v_mfma_f32_16x16x32_bf16 v[120:123], v[120:123], v[16:19], 0
	v_add_u32_e32 v1, v212, v230
	v_add_u32_e32 v2, 0xffffff81, v1
	v_cmp_lt_i32_e32 vcc, v2, v232
	v_mfma_f32_16x16x32_bf16 v[116:119], v[116:119], v[12:15], v[120:123]
	v_cmp_gt_i32_e64 s[0:1], v2, v228
	s_or_b64 vcc, vcc, s[0:1]
	v_cmp_ge_i32_e64 s[0:1], v2, v228
	v_mfma_f32_16x16x32_bf16 v[112:115], v[112:115], v[16:19], 0
	v_mfma_f32_16x16x32_bf16 v[104:107], v[104:107], v[16:19], 0
	s_nop 2
	v_cndmask_b32_e32 v3, v116, v220, vcc
	v_add_u32_e32 v116, 0xffffff82, v1
	v_cmp_lt_i32_e32 vcc, v116, v232
	v_mfma_f32_16x16x32_bf16 v[108:111], v[108:111], v[12:15], v[112:115]
	s_or_b64 vcc, s[0:1], vcc
	v_cndmask_b32_e32 v2, v117, v220, vcc
	s_nop 0
	v_add_u32_e32 v112, 0xffffff83, v1
	v_cmp_lt_i32_e32 vcc, v112, v232
	v_cmp_gt_i32_e64 s[0:1], v112, v228
	s_or_b64 vcc, vcc, s[0:1]
	v_mfma_f32_16x16x32_bf16 v[100:103], v[100:103], v[12:15], v[104:107]
	v_cndmask_b32_e32 v112, v118, v220, vcc
	s_nop 1
	v_add_u32_e32 v104, 0xffffff84, v1
	v_mfma_f32_16x16x32_bf16 v[96:99], v[96:99], v[16:19], 0
	v_cmp_lt_i32_e32 vcc, v104, v232
	v_cmp_gt_i32_e64 s[0:1], v104, v228
	s_or_b64 vcc, vcc, s[0:1]
	v_add_u32_e32 v105, 0xffffff91, v1
	v_cndmask_b32_e32 v104, v119, v220, vcc
	v_cmp_lt_i32_e32 vcc, v105, v232
	v_cmp_gt_i32_e64 s[0:1], v105, v228
	v_mfma_f32_16x16x32_bf16 v[92:95], v[92:95], v[12:15], v[96:99]
	s_or_b64 vcc, vcc, s[0:1]
	v_add_u32_e32 v105, 0xffffffa1, v1
	v_max_f32_e32 v106, v112, v112
	v_add_u32_e32 v97, 0xffffff92, v1
	v_cndmask_b32_e32 v96, v108, v220, vcc
	v_cmp_lt_i32_e32 vcc, v97, v232
	v_cmp_gt_i32_e64 s[0:1], v97, v228
	s_or_b64 vcc, vcc, s[0:1]
	v_add_u32_e32 v98, 0xffffff93, v1
	v_cndmask_b32_e32 v97, v109, v220, vcc
	v_cmp_lt_i32_e32 vcc, v98, v232
	v_cmp_gt_i32_e64 s[0:1], v98, v228
	s_or_b64 vcc, vcc, s[0:1]
	v_add_u32_e32 v99, 0xffffff94, v1
	v_cndmask_b32_e32 v98, v110, v220, vcc
	v_cmp_lt_i32_e32 vcc, v99, v232
	v_cmp_gt_i32_e64 s[0:1], v99, v228
	s_or_b64 vcc, vcc, s[0:1]
	v_cndmask_b32_e32 v99, v111, v220, vcc
	v_cmp_lt_i32_e32 vcc, v105, v232
	v_cmp_gt_i32_e64 s[0:1], v105, v228
	s_or_b64 vcc, vcc, s[0:1]
	v_add_u32_e32 v105, 0xffffffa2, v1
	v_cndmask_b32_e32 v100, v100, v220, vcc
	v_cmp_lt_i32_e32 vcc, v105, v232
	v_cmp_gt_i32_e64 s[0:1], v105, v228
	s_or_b64 vcc, vcc, s[0:1]
	v_add_u32_e32 v105, 0xffffffa3, v1
	v_cndmask_b32_e32 v101, v101, v220, vcc
	v_cmp_lt_i32_e32 vcc, v105, v232
	v_cmp_gt_i32_e64 s[0:1], v105, v228
	s_or_b64 vcc, vcc, s[0:1]
	v_add_u32_e32 v105, 0xffffffa4, v1
	v_cndmask_b32_e32 v102, v102, v220, vcc
	v_cmp_lt_i32_e32 vcc, v105, v232
	v_cmp_gt_i32_e64 s[0:1], v105, v228
	s_or_b64 vcc, vcc, s[0:1]
	v_add_u32_e32 v105, 0xffffffb1, v1
	v_cndmask_b32_e32 v103, v103, v220, vcc
	v_cmp_lt_i32_e32 vcc, v105, v232
	v_cmp_gt_i32_e64 s[0:1], v105, v228
	s_or_b64 vcc, vcc, s[0:1]
	v_add_u32_e32 v105, 0xffffffb2, v1
	v_cndmask_b32_e32 v92, v92, v220, vcc
	v_cmp_lt_i32_e32 vcc, v105, v232
	v_cmp_gt_i32_e64 s[0:1], v105, v228
	s_or_b64 vcc, vcc, s[0:1]
	v_add_u32_e32 v105, 0xffffffb3, v1
	v_cndmask_b32_e32 v93, v93, v220, vcc
	v_cmp_lt_i32_e32 vcc, v105, v232
	v_cmp_gt_i32_e64 s[0:1], v105, v228
	s_or_b64 vcc, vcc, s[0:1]
	v_add_u32_e32 v1, 0xffffffb4, v1
	v_cndmask_b32_e32 v94, v94, v220, vcc
	v_cmp_lt_i32_e32 vcc, v1, v232
	v_cmp_gt_i32_e64 s[0:1], v1, v228
	s_or_b64 vcc, vcc, s[0:1]
	v_cndmask_b32_e32 v1, v95, v220, vcc
	v_max_f32_e32 v95, v2, v2
	v_max_f32_e32 v105, v3, v3
	v_max_f32_e32 v95, v105, v95
	v_max_f32_e32 v105, v104, v104
	v_max_f32_e32 v105, v106, v105
	v_max_f32_e32 v106, v99, v99
	v_max_f32_e32 v107, v98, v98
	v_max_f32_e32 v106, v107, v106
	v_max3_f32 v106, v96, v97, v106
	v_max3_f32 v95, v95, v105, v106
	v_max_f32_e32 v105, v103, v103
	v_max_f32_e32 v106, v102, v102
	v_max_f32_e32 v105, v106, v105
	v_max_f32_e32 v106, v1, v1
	v_max_f32_e32 v107, v94, v94
	v_max_f32_e32 v106, v107, v106
	v_max3_f32 v105, v100, v101, v105
	v_max3_f32 v106, v92, v93, v106
	v_max3_f32 v95, v95, v105, v106
	ds_bpermute_b32 v105, v223, v95
	v_cmp_lt_f32_e32 vcc, s83, v3
	s_waitcnt lgkmcnt(0)
	v_max_f32_e32 v105, v105, v105
	v_max_f32_e32 v95, v95, v105
	ds_bpermute_b32 v105, v224, v95
	s_waitcnt lgkmcnt(0)
	v_max3_f32 v105, v235, v95, v105
	v_sub_f32_e32 v95, v3, v105
	v_exp_f32_e32 v95, v95
	v_sub_f32_e32 v107, v2, v105
	v_exp_f32_e32 v107, v107
	v_sub_f32_e32 v108, v112, v105
	v_exp_f32_e32 v108, v108
	v_cndmask_b32_e32 v3, 0, v95, vcc
	v_cmp_lt_f32_e32 vcc, s83, v2
	v_sub_f32_e32 v109, v96, v105
	v_exp_f32_e32 v109, v109
	v_cndmask_b32_e32 v2, 0, v107, vcc
	v_cmp_lt_f32_e32 vcc, s83, v112
	v_add_f32_e32 v95, 0, v3
	v_add_f32_e32 v95, v2, v95
	v_cndmask_b32_e32 v107, 0, v108, vcc
	v_sub_f32_e32 v108, v104, v105
	v_exp_f32_e32 v108, v108
	v_cmp_lt_f32_e32 vcc, s83, v104
	v_add_f32_e32 v95, v107, v95
	v_sub_f32_e32 v106, v235, v105
	v_cndmask_b32_e32 v104, 0, v108, vcc
	v_cmp_lt_f32_e32 vcc, s83, v96
	v_sub_f32_e32 v96, v97, v105
	v_exp_f32_e32 v96, v96
	v_cndmask_b32_e32 v108, 0, v109, vcc
	v_sub_f32_e32 v109, v98, v105
	v_cmp_lt_f32_e32 vcc, s83, v97
	v_exp_f32_e32 v109, v109
	v_add_f32_e32 v95, v104, v95
	v_cndmask_b32_e32 v97, 0, v96, vcc
	v_sub_f32_e32 v96, v99, v105
	v_exp_f32_e32 v96, v96
	v_add_f32_e32 v95, v108, v95
	v_cmp_lt_f32_e32 vcc, s83, v98
	v_add_f32_e32 v95, v97, v95
	v_mov_b32_e32 v235, v105
	v_cndmask_b32_e32 v98, 0, v109, vcc
	v_cmp_lt_f32_e32 vcc, s83, v99
	v_add_f32_e32 v95, v98, v95
	v_sub_f32_e32 v109, v100, v105
	v_cndmask_b32_e32 v99, 0, v96, vcc
	v_exp_f32_e32 v109, v109
	v_add_f32_e32 v110, v99, v95
	v_sub_f32_e32 v95, v101, v105
	v_exp_f32_e32 v95, v95
	v_sub_f32_e32 v96, v102, v105
	v_cmp_lt_f32_e32 vcc, s83, v100
	v_exp_f32_e32 v96, v96
	s_nop 0
	v_cndmask_b32_e32 v100, 0, v109, vcc
	v_cmp_lt_f32_e32 vcc, s83, v101
	s_nop 1
	v_cndmask_b32_e32 v101, 0, v95, vcc
	v_sub_f32_e32 v95, v103, v105
	v_cmp_lt_f32_e32 vcc, s83, v102
	v_exp_f32_e32 v95, v95
	s_nop 0
	v_cndmask_b32_e32 v102, 0, v96, vcc
	v_sub_f32_e32 v96, v92, v105
	v_exp_f32_e32 v96, v96
	v_cmp_lt_f32_e32 vcc, s83, v103
	s_nop 1
	v_cndmask_b32_e32 v103, 0, v95, vcc
	v_cmp_lt_f32_e32 vcc, s83, v92
	v_sub_f32_e32 v92, v93, v105
	v_exp_f32_e32 v92, v92
	v_sub_f32_e32 v95, v94, v105
	v_cndmask_b32_e32 v109, 0, v96, vcc
	v_exp_f32_e32 v95, v95
	v_exp_f32_e32 v96, v106
	v_cmp_lt_f32_e32 vcc, s83, v93
	v_cvt_pk_bf16_f32 v93, v107, v104
	v_pk_mul_f32 v[22:23], v[22:23], v[96:97] op_sel_hi:[1,0]
	v_cndmask_b32_e32 v106, 0, v92, vcc
	v_cmp_lt_f32_e32 vcc, s83, v94
	v_cvt_pk_bf16_f32 v92, v3, v2
	v_cvt_pk_bf16_f32 v94, v108, v97
	v_cndmask_b32_e32 v111, 0, v95, vcc
	v_cvt_pk_bf16_f32 v95, v98, v99
	v_sub_f32_e32 v2, v1, v105
	v_pk_mul_f32 v[20:21], v[20:21], v[96:97] op_sel_hi:[1,0]
	v_pk_mul_f32 v[6:7], v[6:7], v[96:97] op_sel_hi:[1,0]
	v_pk_mul_f32 v[4:5], v[4:5], v[96:97] op_sel_hi:[1,0]
	v_mfma_f32_16x16x32_bf16 v[20:23], v[52:55], v[92:95], v[20:23]
	v_exp_f32_e32 v52, v2
	v_pk_mul_f32 v[46:47], v[46:47], v[96:97] op_sel_hi:[1,0]
	v_pk_mul_f32 v[44:45], v[44:45], v[96:97] op_sel_hi:[1,0]
	v_mfma_f32_16x16x32_bf16 v[2:5], v[48:51], v[92:95], v[4:7]
	v_mul_f32_e64 v10, v10, v96
	v_mul_f32_e64 v11, v11, v96
	v_pk_mul_f32 v[8:9], v[8:9], v[96:97] op_sel_hi:[1,0]
	v_cmp_lt_f32_e32 vcc, s83, v1
	v_add_f32_e32 v6, v100, v110
	v_mfma_f32_16x16x32_bf16 v[44:47], v[56:59], v[92:95], v[44:47]
	v_add_f32_e32 v6, v101, v6
	v_add_f32_e32 v6, v102, v6
	v_cndmask_b32_e32 v1, 0, v52, vcc
	v_mfma_f32_16x16x32_bf16 v[8:11], v[40:43], v[92:95], v[8:11]
	v_add_f32_e32 v6, v103, v6
	v_cvt_pk_bf16_f32 v40, v100, v101
	v_cvt_pk_bf16_f32 v41, v102, v103
	v_cvt_pk_bf16_f32 v42, v109, v106
	v_cvt_pk_bf16_f32 v43, v111, v1
	v_add_f32_e32 v6, v109, v6
	s_nop 0
	v_mfma_f32_16x16x32_bf16 v[44:47], v[36:39], v[40:43], v[44:47]
	v_mfma_f32_16x16x32_bf16 v[20:23], v[32:35], v[40:43], v[20:23]
	v_add_f32_e32 v32, v106, v6
	v_mfma_f32_16x16x32_bf16 v[4:7], v[28:31], v[40:43], v[2:5]
	v_mfma_f32_16x16x32_bf16 v[8:11], v[24:27], v[40:43], v[8:11]
	s_nop 1
	v_add_f32_e32 v2, v111, v32
	v_add_f32_e32 v234, v1, v2
	v_fmac_f32_e32 v234, v236, v96
.Lwin_join:
	v_mov_b32_e32 v236, v234
.Lwin_skip:
	s_mov_b32 s93, s36
	s_mov_b32 s36, s37
	s_mov_b32 s37, s72
	s_mov_b32 s72, s93
	s_add_i32 s12, s12, 1
	s_cmp_le_i32 s12, s13
	s_cbranch_scc1 .Lwin_loop
	s_branch .LBB0_422
